# DF late half: priority raised from the step barrier release until its operand reads are issued (6.4 start-of-segment penalty)
# baseline (speedup 1.0000x reference)
.LBB0_402:
	s_setprio 1
	s_and_b32 s8, s26, 8
	s_add_i32 s8, s8, 0
	s_add_i32 s8, s8, 0x241c0
	v_mov_b32_e32 v0, s8
	ds_read_b64 v[14:15], v0
	s_cmp_lt_i32 s12, 3
	s_cbranch_scc1 .LBB0_404
	s_and_b32 s13, s27, 0xc000
	s_cmp_gt_i32 s24, 1
	s_cselect_b32 s8, -2, 3
	s_add_i32 s8, s8, s24
	s_lshl_b32 s14, s8, 14
	s_lshl_b64 s[8:9], s[80:81], 14
	v_lshl_add_u64 v[80:81], v[180:181], 0, s[8:9]
	s_add_i32 s13, s76, s13
	s_mov_b32 s15, m0
	s_mov_b32 m0, s13
	s_nop 0
	global_load_lds_dwordx4 v[80:81], off
	s_mov_b32 m0, s15
	v_lshl_add_u64 v[80:81], v[80:81], 0, s[88:89]
	s_addk_i32 s13, 0x2000
	s_mov_b32 s15, m0
	s_mov_b32 m0, s13
	s_nop 0
	global_load_lds_dwordx4 v[80:81], off
	s_mov_b32 m0, s15
	v_lshl_add_u64 v[80:81], v[182:183], 0, s[8:9]
	s_add_i32 s8, s31, s14
	s_mov_b32 s9, m0
	s_mov_b32 m0, s8
	s_nop 0
	global_load_lds_dwordx4 v[80:81], off
	s_mov_b32 m0, s9
	v_lshl_add_u64 v[80:81], v[80:81], 0, s[88:89]
	s_addk_i32 s8, 0x2000
	s_mov_b32 s9, m0
	s_mov_b32 m0, s8
	s_nop 0
	global_load_lds_dwordx4 v[80:81], off
	s_mov_b32 m0, s9
.LBB0_404:
	s_mov_b32 s97, s96
	s_waitcnt lgkmcnt(0)
	v_cmp_eq_u64_e64 s[8:9], s[96:97], v[14:15]
	s_and_b64 vcc, exec, s[8:9]
	s_cbranch_vccnz .LBB0_420
	s_cmp_gt_i32 s12, s21
	s_cbranch_scc1 .LBB0_417
	s_xor_b64 s[12:13], s[10:11], -1
	s_add_i32 s10, s27, 0xffff4000
	s_and_b32 s10, s10, 0xc000
	s_add_i32 s14, s34, s10
	v_add_u32_e32 v0, s14, v222
	s_mov_b64 s[10:11], -1
	s_and_b64 vcc, exec, s[12:13]
	v_add_u32_e32 v202, v0, v223
	v_add_u32_e32 v15, v0, v224
	v_add_u32_e32 v14, v0, v225
	v_add_u32_e32 v0, v0, v233
	s_cbranch_vccz .LBB0_408
	ds_read_b128 v[80:83], v202
	ds_read_b128 v[84:87], v202 offset:4096
	ds_read_b128 v[148:151], v15
	ds_read_b128 v[204:207], v15 offset:4096
	ds_read_b128 v[208:211], v14
	ds_read_b128 v[212:215], v14 offset:4096
	ds_read_b128 v[238:241], v0
	ds_read_b128 v[242:245], v0 offset:4096
	s_setprio 0
	s_waitcnt lgkmcnt(7)
	v_mfma_f32_32x32x16_bf16 v[96:111], v[80:83], v[136:139], 0
	s_mov_b64 s[10:11], 0
	s_waitcnt lgkmcnt(6)
	v_mfma_f32_32x32x16_bf16 v[80:95], v[84:87], v[136:139], 0
	s_waitcnt lgkmcnt(5)
	v_mfma_f32_32x32x16_bf16 v[96:111], v[148:151], v[128:131], v[96:111]
	s_waitcnt lgkmcnt(4)
	v_mfma_f32_32x32x16_bf16 v[80:95], v[204:207], v[128:131], v[80:95]
	s_waitcnt lgkmcnt(3)
	v_mfma_f32_32x32x16_bf16 v[96:111], v[208:211], v[140:143], v[96:111]
	s_waitcnt lgkmcnt(2)
	v_mfma_f32_32x32x16_bf16 v[80:95], v[212:215], v[140:143], v[80:95]
	s_waitcnt lgkmcnt(1)
	v_mfma_f32_32x32x16_bf16 v[96:111], v[238:241], v[132:135], v[96:111]
	s_waitcnt lgkmcnt(0)
	v_mfma_f32_32x32x16_bf16 v[80:95], v[242:245], v[132:135], v[80:95]
.LBB0_408:
	s_andn2_b64 vcc, exec, s[10:11]
	s_cbranch_vccnz .LBB0_410
	s_lshl_b32 s10, s24, 14
	s_addk_i32 s10, 0xc000
	s_cmp_gt_i32 s24, 0
	s_cselect_b32 s10, s10, 0x10000
	v_add_u32_e32 v203, s10, v221
	s_nop 4
	ds_read_b64_tr_b16 v[80:81], v203
	ds_read_b64_tr_b16 v[82:83], v203 offset:512
	ds_read_b64_tr_b16 v[84:85], v203 offset:1024
	ds_read_b64_tr_b16 v[86:87], v203 offset:1536
	ds_read_b64_tr_b16 v[88:89], v203 offset:4096
	ds_read_b64_tr_b16 v[90:91], v203 offset:4608
	ds_read_b64_tr_b16 v[92:93], v203 offset:5120
	ds_read_b64_tr_b16 v[94:95], v203 offset:5632
	ds_read_b64_tr_b16 v[96:97], v203 offset:2048
	ds_read_b64_tr_b16 v[98:99], v203 offset:2560
	ds_read_b64_tr_b16 v[100:101], v203 offset:3072
	ds_read_b64_tr_b16 v[102:103], v203 offset:3584
	ds_read_b64_tr_b16 v[104:105], v203 offset:6144
	ds_read_b64_tr_b16 v[106:107], v203 offset:6656
	ds_read_b64_tr_b16 v[108:109], v203 offset:7168
	ds_read_b64_tr_b16 v[110:111], v203 offset:7680
	ds_read_b128 v[204:207], v202
	ds_read_b128 v[208:211], v202 offset:4096
	ds_read_b128 v[212:215], v15
	ds_read_b128 v[238:241], v15 offset:4096
	ds_read_b128 v[242:245], v14
	v_mov_b32_e32 v202, v246
	ds_read_b128 v[246:249], v14 offset:4096
	ds_read_b128 v[250:253], v0
	ds_read_b128 v[148:151], v0 offset:4096
	s_setprio 0
	s_waitcnt lgkmcnt(14)
	v_mfma_f32_32x32x16_bf16 v[64:79], v[80:83], v[144:147], v[64:79]
	ds_read_b64_tr_b16 v[80:81], v203 offset:8192
	ds_read_b64_tr_b16 v[82:83], v203 offset:8704
	v_mfma_f32_32x32x16_bf16 v[48:63], v[88:91], v[144:147], v[48:63]
	ds_read_b64_tr_b16 v[88:89], v203 offset:12288
	ds_read_b64_tr_b16 v[90:91], v203 offset:12800
	v_mfma_f32_32x32x16_bf16 v[64:79], v[84:87], v[10:13], v[64:79]
	ds_read_b64_tr_b16 v[84:85], v203 offset:9216
	ds_read_b64_tr_b16 v[86:87], v203 offset:9728
	v_mfma_f32_32x32x16_bf16 v[48:63], v[92:95], v[10:13], v[48:63]
	ds_read_b64_tr_b16 v[92:93], v203 offset:13312
	ds_read_b64_tr_b16 v[94:95], v203 offset:13824
	v_mfma_f32_32x32x16_bf16 v[64:79], v[96:99], v[6:9], v[64:79]
	ds_read_b64_tr_b16 v[96:97], v203 offset:10240
	ds_read_b64_tr_b16 v[98:99], v203 offset:10752
	s_waitcnt lgkmcnt(10)
	v_mfma_f32_32x32x16_bf16 v[48:63], v[104:107], v[6:9], v[48:63]
	ds_read_b64_tr_b16 v[104:105], v203 offset:14336
	ds_read_b64_tr_b16 v[106:107], v203 offset:14848
	v_mfma_f32_32x32x16_bf16 v[64:79], v[100:103], v[2:5], v[64:79]
	ds_read_b64_tr_b16 v[100:101], v203 offset:11264
	ds_read_b64_tr_b16 v[102:103], v203 offset:11776
	v_mfma_f32_32x32x16_bf16 v[48:63], v[108:111], v[2:5], v[48:63]
	ds_read_b64_tr_b16 v[108:109], v203 offset:15360
	ds_read_b64_tr_b16 v[110:111], v203 offset:15872
	s_waitcnt lgkmcnt(14)
	v_mfma_f32_32x32x16_bf16 v[32:47], v[80:83], v[144:147], v[32:47]
	s_waitcnt lgkmcnt(12)
	v_mfma_f32_32x32x16_bf16 v[16:31], v[88:91], v[144:147], v[16:31]
	s_waitcnt lgkmcnt(10)
	v_mfma_f32_32x32x16_bf16 v[32:47], v[84:87], v[10:13], v[32:47]
	s_waitcnt lgkmcnt(8)
	v_mfma_f32_32x32x16_bf16 v[16:31], v[92:95], v[10:13], v[16:31]
	s_waitcnt lgkmcnt(6)
	v_mfma_f32_32x32x16_bf16 v[32:47], v[96:99], v[6:9], v[32:47]
	s_waitcnt lgkmcnt(4)
	v_mfma_f32_32x32x16_bf16 v[16:31], v[104:107], v[6:9], v[16:31]
	s_waitcnt lgkmcnt(2)
	v_mfma_f32_32x32x16_bf16 v[32:47], v[100:103], v[2:5], v[32:47]
	s_waitcnt lgkmcnt(0)
	v_mfma_f32_32x32x16_bf16 v[16:31], v[108:111], v[2:5], v[16:31]
	v_mfma_f32_32x32x16_bf16 v[96:111], v[204:207], v[136:139], 0
	v_mfma_f32_32x32x16_bf16 v[80:95], v[208:211], v[136:139], 0
	v_mfma_f32_32x32x16_bf16 v[96:111], v[212:215], v[128:131], v[96:111]
	v_mfma_f32_32x32x16_bf16 v[80:95], v[238:241], v[128:131], v[80:95]
	v_mfma_f32_32x32x16_bf16 v[96:111], v[242:245], v[140:143], v[96:111]
	v_mfma_f32_32x32x16_bf16 v[80:95], v[246:249], v[140:143], v[80:95]
	v_mov_b32_e32 v246, v202
	v_mfma_f32_32x32x16_bf16 v[96:111], v[250:253], v[132:135], v[96:111]
	v_mfma_f32_32x32x16_bf16 v[80:95], v[148:151], v[132:135], v[80:95]

.LBB0_417:
	s_setprio 0
	v_add_u32_e32 v0, 1, v236
	v_cvt_f32_i32_e32 v0, v0
	s_mov_b64 s[12:13], exec
	v_fma_f32 v0, v234, v0, s20
	v_sub_f32_e32 v0, v0, v237
	v_cmp_gt_f32_e32 vcc, s52, v0
	s_and_saveexec_b64 s[14:15], s[86:87]
	s_cbranch_execz .LBB0_419
	s_add_i32 s28, s26, -8
	s_and_b32 s28, s28, 8
	s_add_i32 s28, s68, s28
	s_cmp_eq_u64 vcc, s[12:13]
	s_cselect_b64 s[12:13], -1, 0
	v_cndmask_b32_e64 v0, 0, 1, s[12:13]
	v_mov_b32_e32 v14, s28
	ds_write_b8 v14, v0

.LBB0_420:
	s_setprio 0
	v_add_u32_e32 v236, 64, v236
	s_add_i32 s80, s80, -1
	s_add_i32 s26, s26, 8
	s_addk_i32 s27, 0x4000
	s_and_b64 vcc, exec, s[8:9]
	s_cbranch_vccz .LBB0_393
